# attention epilogue: four subln_g loads issued together
# baseline (speedup 1.0000x reference)
; __device__ __forceinline__ float shx(float v, int o, int lane) { return __int_as_float(__builtin_amdgcn_ds_bpermute((lane ^ o) << 2, __float_as_int(v))); }
; __device__ __forceinline__ int crow(int r, int hi) { return (r & 3) + 8 * (r >> 2) + 4 * hi; }
; __device__ __forceinline__ void attn_unit(LAS unsigned char* lds, bf16_t* Zg, const unsigned char* KVg, int S, int b, int h, int qb, const float* lq1, const float* lk1, const float* lq2, const float* lk2, const float* subln_g, const float* rel_bias, bool dostore = true) {
;     ...
;     if (mp == 0) {
;         float ss[16];
; #pragma unroll
;         for (int r = 0; r < 16; ++r) { float a = 0.f;
; #pragma unroll
;             for (int db = 0; db < 4; ++db) { const float d = o[db][r] * inv[r] - exch[(32 * qsub + crow(r, hi)) * 128 + db * 32 + r32]; o[db][r] = d; a += d * d; }
;             ss[r] = a; }
; #pragma unroll
;         for (int r = 0; r < 16; ++r) {
; #pragma unroll
;             for (int sft = 1; sft < 32; sft <<= 1) ss[r] += shx(ss[r], sft, lane);
.LBB0_287:
	s_cmpk_gt_u32 s15, 0xff
	s_waitcnt lgkmcnt(0)
	s_barrier
	s_cbranch_scc1 .LBB0_187
	v_or_b32_e32 v0, s84, v211
	v_lshlrev_b32_e32 v0, 9, v0
	v_add3_u32 v0, 0, v82, v0
	ds_read2_b32 v[90:91], v0 offset1:32
	s_waitcnt lgkmcnt(0)
	v_fma_f32 v83, v50, v78, -v90
	v_fma_f32 v50, v34, v78, -v91
	ds_read2_b32 v[90:91], v0 offset0:64 offset1:96
	v_mul_f32_e32 v102, v50, v50
	v_fmac_f32_e32 v102, v83, v83
	s_waitcnt lgkmcnt(0)
	v_fma_f32 v34, v18, v78, -v90
	v_fma_f32 v2, v2, v78, -v91
	ds_read2_b32 v[90:91], v0 offset0:128 offset1:160
	v_add_u32_e32 v18, 0x400, v0
	v_fmac_f32_e32 v102, v34, v34
	v_fmac_f32_e32 v102, v2, v2
	s_waitcnt lgkmcnt(0)
	v_fma_f32 v78, v51, v79, -v90
	v_fma_f32 v51, v35, v79, -v91
	ds_read2_b32 v[90:91], v0 offset0:192 offset1:224
	v_mul_f32_e32 v101, v51, v51
	v_fmac_f32_e32 v101, v78, v78
	s_waitcnt lgkmcnt(0)
	v_fma_f32 v35, v19, v79, -v90
	v_fma_f32 v3, v3, v79, -v91
	ds_read2_b32 v[90:91], v18 offset1:32
	v_add_u32_e32 v19, 0x1000, v0
	v_fmac_f32_e32 v101, v35, v35
	v_fmac_f32_e32 v101, v3, v3
	s_waitcnt lgkmcnt(0)
	v_fma_f32 v79, v52, v80, -v90
	v_fma_f32 v52, v36, v80, -v91
	ds_read2_b32 v[90:91], v18 offset0:64 offset1:96
	v_mul_f32_e32 v100, v52, v52
	v_fmac_f32_e32 v100, v79, v79
	s_waitcnt lgkmcnt(0)
	v_fma_f32 v36, v20, v80, -v90
	v_fma_f32 v4, v4, v80, -v91
	ds_read2_b32 v[90:91], v18 offset0:128 offset1:160
	v_fmac_f32_e32 v100, v36, v36
	v_fmac_f32_e32 v100, v4, v4
	s_waitcnt lgkmcnt(0)
	v_fma_f32 v80, v53, v81, -v90
	v_fma_f32 v53, v37, v81, -v91
	ds_read2_b32 v[90:91], v18 offset0:192 offset1:224
	v_mul_f32_e32 v99, v53, v53
	v_fmac_f32_e32 v99, v80, v80
	s_waitcnt lgkmcnt(0)
	v_fma_f32 v37, v21, v81, -v90
	ds_read2_b32 v[20:21], v19 offset1:32
	v_fma_f32 v5, v5, v81, -v91
	v_fmac_f32_e32 v99, v37, v37
	v_fmac_f32_e32 v99, v5, v5
	s_waitcnt lgkmcnt(0)
	v_fma_f32 v81, v54, v74, -v20
	v_fma_f32 v54, v38, v74, -v21
	ds_read2_b32 v[20:21], v19 offset0:64 offset1:96
	v_mul_f32_e32 v98, v54, v54
	v_fmac_f32_e32 v98, v81, v81
	s_waitcnt lgkmcnt(0)
	v_fma_f32 v38, v22, v74, -v20
	v_fma_f32 v6, v6, v74, -v21
	ds_read2_b32 v[20:21], v19 offset0:128 offset1:160
	v_fmac_f32_e32 v98, v38, v38
	v_fmac_f32_e32 v98, v6, v6
	s_waitcnt lgkmcnt(0)
	v_fma_f32 v74, v55, v75, -v20
	v_fma_f32 v55, v39, v75, -v21
	ds_read2_b32 v[20:21], v19 offset0:192 offset1:224
	v_mul_f32_e32 v97, v55, v55
	v_fmac_f32_e32 v97, v74, v74
	s_waitcnt lgkmcnt(0)
	v_fma_f32 v39, v23, v75, -v20
	v_add_u32_e32 v20, 0x1400, v0
	ds_read2_b32 v[22:23], v20 offset1:32
	v_fma_f32 v7, v7, v75, -v21
	v_add_u32_e32 v21, 0x2000, v0
	v_fmac_f32_e32 v97, v39, v39
	v_fmac_f32_e32 v97, v7, v7
	s_waitcnt lgkmcnt(0)
	v_fma_f32 v75, v56, v76, -v22
	v_fma_f32 v56, v40, v76, -v23
	ds_read2_b32 v[22:23], v20 offset0:64 offset1:96
	v_mul_f32_e32 v96, v56, v56
	v_fmac_f32_e32 v96, v75, v75
	s_waitcnt lgkmcnt(0)
	v_fma_f32 v40, v24, v76, -v22
	v_fma_f32 v8, v8, v76, -v23
	ds_read2_b32 v[22:23], v20 offset0:128 offset1:160
	v_fmac_f32_e32 v96, v40, v40
	v_fmac_f32_e32 v96, v8, v8
	s_waitcnt lgkmcnt(0)
	v_fma_f32 v76, v57, v77, -v22
	v_fma_f32 v57, v41, v77, -v23
	ds_read2_b32 v[22:23], v20 offset0:192 offset1:224
	v_mul_f32_e32 v95, v57, v57
	v_fmac_f32_e32 v95, v76, v76
	s_waitcnt lgkmcnt(0)
	v_fma_f32 v25, v25, v77, -v22
	v_fma_f32 v9, v9, v77, -v23
	ds_read2_b32 v[22:23], v21 offset1:32
	v_fmac_f32_e32 v95, v25, v25
	v_fmac_f32_e32 v95, v9, v9
	s_waitcnt lgkmcnt(0)
	v_fma_f32 v77, v58, v70, -v22
	v_fma_f32 v58, v42, v70, -v23
	ds_read2_b32 v[22:23], v21 offset0:64 offset1:96
	v_mul_f32_e32 v90, v58, v58
	v_fmac_f32_e32 v90, v77, v77
	s_waitcnt lgkmcnt(0)
	v_fma_f32 v26, v26, v70, -v22
	v_fma_f32 v10, v10, v70, -v23
	ds_read2_b32 v[22:23], v21 offset0:128 offset1:160
	v_fmac_f32_e32 v90, v26, v26
	v_fmac_f32_e32 v90, v10, v10
	s_waitcnt lgkmcnt(0)
	v_fma_f32 v70, v59, v71, -v22
	v_fma_f32 v43, v43, v71, -v23
	ds_read2_b32 v[22:23], v21 offset0:192 offset1:224
	v_mul_f32_e32 v93, v43, v43
	v_fmac_f32_e32 v93, v70, v70
	s_waitcnt lgkmcnt(0)
	v_fma_f32 v41, v27, v71, -v22
	v_add_u32_e32 v22, 0x2400, v0
	ds_read2_b32 v[104:105], v22 offset1:32
	v_fma_f32 v11, v11, v71, -v23
	v_add_u32_e32 v23, 0x3000, v0
	ds_bpermute_b32 v27, v84, v102
	v_fmac_f32_e32 v93, v41, v41
	s_waitcnt lgkmcnt(1)
	v_fma_f32 v71, v60, v72, -v104
	v_fma_f32 v59, v44, v72, -v105
	ds_read2_b32 v[104:105], v22 offset0:64 offset1:96
	s_waitcnt lgkmcnt(1)
	v_add_f32_e32 v27, v102, v27
	v_fmac_f32_e32 v93, v11, v11
	v_mul_f32_e32 v94, v59, v59
	v_fmac_f32_e32 v94, v71, v71
	s_waitcnt lgkmcnt(0)
	v_fma_f32 v28, v28, v72, -v104
	v_fma_f32 v12, v12, v72, -v105
	ds_read2_b32 v[104:105], v22 offset0:128 offset1:160
	v_fmac_f32_e32 v94, v28, v28
	v_fmac_f32_e32 v94, v12, v12
	s_waitcnt lgkmcnt(0)
	v_fma_f32 v61, v61, v73, -v104
	v_fma_f32 v45, v45, v73, -v105
	ds_read2_b32 v[104:105], v22 offset0:192 offset1:224
	v_mul_f32_e32 v92, v45, v45
	v_fmac_f32_e32 v92, v61, v61
	s_waitcnt lgkmcnt(0)
	v_fma_f32 v29, v29, v73, -v104
	v_fma_f32 v13, v13, v73, -v105
	ds_read2_b32 v[104:105], v23 offset0:64 offset1:96
	ds_read2_b32 v[72:73], v23 offset1:32
	v_fmac_f32_e32 v92, v29, v29
	v_fmac_f32_e32 v92, v13, v13
	s_waitcnt lgkmcnt(1)
	v_fma_f32 v42, v30, v66, -v104
	ds_bpermute_b32 v30, v85, v27
	v_fma_f32 v14, v14, v66, -v105
	ds_read2_b32 v[104:105], v23 offset0:128 offset1:160
	s_waitcnt lgkmcnt(2)
	v_fma_f32 v72, v62, v66, -v72
	v_fma_f32 v46, v46, v66, -v73
	s_waitcnt lgkmcnt(1)
	v_add_f32_e32 v27, v27, v30
	ds_bpermute_b32 v30, v86, v27
	s_waitcnt lgkmcnt(1)
	v_fma_f32 v63, v63, v67, -v104
	v_fma_f32 v60, v47, v67, -v105
	ds_read2_b32 v[104:105], v23 offset0:192 offset1:224
	v_mul_f32_e32 v91, v46, v46
	s_waitcnt lgkmcnt(1)
; __device__ __forceinline__ float shx(float v, int o, int lane) { return __int_as_float(__builtin_amdgcn_ds_bpermute((lane ^ o) << 2, __float_as_int(v))); }
; __device__ __forceinline__ void attn_unit(LAS unsigned char* lds, bf16_t* Zg, const unsigned char* KVg, int S, int b, int h, int qb, const float* lq1, const float* lk1, const float* lq2, const float* lk2, const float* subln_g, const float* rel_bias, bool dostore = true) {
;     ...
;         for (int r = 0; r < 16; ++r) {
; #pragma unroll
;             for (int sft = 1; sft < 32; sft <<= 1) ss[r] += shx(ss[r], sft, lane);
;             ss[r] = (1.0f - LAMBDA_INIT) / sqrtf(ss[r] * (1.0f / 128.0f) + EPS); }
	v_add_f32_e32 v27, v27, v30
	ds_bpermute_b32 v30, v87, v27
	v_fmac_f32_e32 v91, v72, v72
	s_waitcnt lgkmcnt(1)
	v_fma_f32 v24, v15, v67, -v105
	v_add_u32_e32 v15, 0x3400, v0
	v_fma_f32 v31, v31, v67, -v104
	s_waitcnt lgkmcnt(0)
	v_add_f32_e32 v27, v27, v30
	ds_bpermute_b32 v30, v88, v27
	ds_read2_b32 v[66:67], v15 offset1:32
	v_fmac_f32_e32 v91, v42, v42
	v_fmac_f32_e32 v91, v14, v14
	v_mul_f32_e32 v89, v60, v60
	s_waitcnt lgkmcnt(1)
	v_add_f32_e32 v27, v27, v30
	v_fmamk_f32 v27, v27, 0x3c000000, v206
	v_cmp_gt_f32_e32 vcc, s36, v27
	v_mul_f32_e32 v30, 0x4f800000, v27
	s_waitcnt lgkmcnt(0)
	v_fma_f32 v64, v64, v68, -v66
	v_cndmask_b32_e32 v27, v27, v30, vcc
	v_sqrt_f32_e32 v30, v27
	v_fma_f32 v48, v48, v68, -v67
	ds_read2_b32 v[66:67], v15 offset0:64 offset1:96
	v_fmac_f32_e32 v89, v63, v63
	v_add_u32_e32 v44, -1, v30
	v_fma_f32 v47, -v44, v30, v27
	v_cmp_ge_f32_e64 s[4:5], 0, v47
	v_add_u32_e32 v47, 1, v30
	s_waitcnt lgkmcnt(0)
	v_fma_f32 v32, v32, v68, -v66
	v_cndmask_b32_e64 v44, v30, v44, s[4:5]
	v_fma_f32 v30, -v47, v30, v27
	v_cmp_lt_f32_e64 s[4:5], 0, v30
	v_fma_f32 v16, v16, v68, -v67
	ds_read2_b32 v[66:67], v15 offset0:128 offset1:160
	v_cndmask_b32_e64 v30, v44, v47, s[4:5]
	v_mul_f32_e32 v44, 0x37800000, v30
	v_cndmask_b32_e32 v30, v30, v44, vcc
	v_cmp_class_f32_e32 vcc, v27, v205
	s_waitcnt lgkmcnt(0)
	v_fma_f32 v65, v65, v69, -v66
	v_fma_f32 v49, v49, v69, -v67
	v_cndmask_b32_e32 v27, v30, v27, vcc
	v_div_scale_f32 v30, s[4:5], v27, v27, s95
	v_rcp_f32_e32 v44, v30
	ds_read2_b32 v[66:67], v15 offset0:192 offset1:224
	v_fmac_f32_e32 v89, v31, v31
	v_fmac_f32_e32 v89, v24, v24
	v_fma_f32 v47, -v30, v44, 1.0
	v_fmac_f32_e32 v44, v47, v44
	v_div_scale_f32 v47, vcc, s95, v27, s95
	v_mul_f32_e32 v62, v47, v44
	s_waitcnt lgkmcnt(0)
	v_fma_f32 v33, v33, v69, -v66
	v_fma_f32 v66, -v30, v62, v47
	v_fmac_f32_e32 v62, v66, v44
	v_fma_f32 v30, -v30, v62, v47
	v_div_fmas_f32 v30, v30, v44, v62
	v_div_fixup_f32 v27, v30, v27, s95
	ds_bpermute_b32 v30, v84, v101
	v_fma_f32 v17, v17, v69, -v67
	v_mul_f32_e32 v73, v48, v48
	v_fmac_f32_e32 v73, v64, v64
	v_fmac_f32_e32 v73, v32, v32
	s_waitcnt lgkmcnt(0)
	v_add_f32_e32 v30, v101, v30
	ds_bpermute_b32 v44, v85, v30
	v_fmac_f32_e32 v73, v16, v16
	v_mul_f32_e32 v68, v49, v49
	v_fmac_f32_e32 v68, v65, v65
	v_fmac_f32_e32 v68, v33, v33
	s_waitcnt lgkmcnt(0)
	v_add_f32_e32 v30, v30, v44
	ds_bpermute_b32 v44, v86, v30
	v_fmac_f32_e32 v68, v17, v17
	v_mul_f32_e32 v83, v83, v27
	v_mul_f32_e32 v50, v50, v27
	v_mul_f32_e32 v34, v34, v27
	s_waitcnt lgkmcnt(0)
	v_add_f32_e32 v30, v30, v44
	ds_bpermute_b32 v44, v87, v30
	v_mul_f32_e32 v2, v2, v27
	s_waitcnt lgkmcnt(0)
	v_add_f32_e32 v30, v30, v44
	ds_bpermute_b32 v44, v88, v30
	s_waitcnt lgkmcnt(0)
	v_add_f32_e32 v30, v30, v44
	v_fmamk_f32 v30, v30, 0x3c000000, v206
	v_cmp_gt_f32_e32 vcc, s36, v30
	v_mul_f32_e32 v44, 0x4f800000, v30
	s_nop 0
	v_cndmask_b32_e32 v30, v30, v44, vcc
	v_sqrt_f32_e32 v44, v30
	s_nop 0
	v_add_u32_e32 v47, -1, v44
	v_fma_f32 v62, -v47, v44, v30
	v_cmp_ge_f32_e64 s[4:5], 0, v62
	v_add_u32_e32 v62, 1, v44
	s_nop 0
	v_cndmask_b32_e64 v47, v44, v47, s[4:5]
	v_fma_f32 v44, -v62, v44, v30
	v_cmp_lt_f32_e64 s[4:5], 0, v44
	s_nop 1
	v_cndmask_b32_e64 v44, v47, v62, s[4:5]
	v_mul_f32_e32 v47, 0x37800000, v44
	v_cndmask_b32_e32 v44, v44, v47, vcc
	v_cmp_class_f32_e32 vcc, v30, v205
	s_nop 1
	v_cndmask_b32_e32 v30, v44, v30, vcc
	v_div_scale_f32 v44, s[4:5], v30, v30, s95
	v_rcp_f32_e32 v47, v44
	s_nop 0
	v_fma_f32 v62, -v44, v47, 1.0
	v_fmac_f32_e32 v47, v62, v47
	v_div_scale_f32 v62, vcc, s95, v30, s95
	v_mul_f32_e32 v66, v62, v47
	v_fma_f32 v67, -v44, v66, v62
	v_fmac_f32_e32 v66, v67, v47
	v_fma_f32 v44, -v44, v66, v62
	v_div_fmas_f32 v44, v44, v47, v66
	v_div_fixup_f32 v30, v44, v30, s95
	ds_bpermute_b32 v44, v84, v100
	v_mul_f32_e32 v78, v78, v30
	s_waitcnt lgkmcnt(0)
	v_add_f32_e32 v44, v100, v44
	ds_bpermute_b32 v47, v85, v44
	s_waitcnt lgkmcnt(0)
	v_add_f32_e32 v44, v44, v47
	ds_bpermute_b32 v47, v86, v44
	s_waitcnt lgkmcnt(0)
	v_add_f32_e32 v44, v44, v47
	ds_bpermute_b32 v47, v87, v44
	s_waitcnt lgkmcnt(0)
	v_add_f32_e32 v44, v44, v47
	ds_bpermute_b32 v47, v88, v44
	s_waitcnt lgkmcnt(0)
	v_add_f32_e32 v44, v44, v47
	v_fmamk_f32 v44, v44, 0x3c000000, v206
	v_cmp_gt_f32_e32 vcc, s36, v44
	v_mul_f32_e32 v47, 0x4f800000, v44
	s_nop 0
	v_cndmask_b32_e32 v44, v44, v47, vcc
	v_sqrt_f32_e32 v47, v44
	s_nop 0
	v_add_u32_e32 v62, -1, v47
	v_fma_f32 v66, -v62, v47, v44
	v_cmp_ge_f32_e64 s[4:5], 0, v66
	v_add_u32_e32 v66, 1, v47
	s_nop 0
	v_cndmask_b32_e64 v62, v47, v62, s[4:5]
	v_fma_f32 v47, -v66, v47, v44
	v_cmp_lt_f32_e64 s[4:5], 0, v47
	s_nop 1
	v_cndmask_b32_e64 v47, v62, v66, s[4:5]
	v_mul_f32_e32 v62, 0x37800000, v47
	v_cndmask_b32_e32 v47, v47, v62, vcc
	v_cmp_class_f32_e32 vcc, v44, v205
	s_nop 1
	v_cndmask_b32_e32 v44, v47, v44, vcc
	v_div_scale_f32 v47, s[4:5], v44, v44, s95
	v_rcp_f32_e32 v62, v47
	s_nop 0
	v_fma_f32 v66, -v47, v62, 1.0
	v_fmac_f32_e32 v62, v66, v62
	v_div_scale_f32 v66, vcc, s95, v44, s95
	v_mul_f32_e32 v67, v66, v62
	v_fma_f32 v69, -v47, v67, v66
	v_fmac_f32_e32 v67, v69, v62
	v_fma_f32 v47, -v47, v67, v66
	v_div_fmas_f32 v47, v47, v62, v67
	v_div_fixup_f32 v44, v47, v44, s95
	ds_bpermute_b32 v47, v84, v99
	v_mul_f32_e32 v79, v79, v44
	s_waitcnt lgkmcnt(0)
	v_add_f32_e32 v47, v99, v47
	ds_bpermute_b32 v62, v85, v47
	s_waitcnt lgkmcnt(0)
	v_add_f32_e32 v47, v47, v62
	ds_bpermute_b32 v62, v86, v47
	s_waitcnt lgkmcnt(0)
	v_add_f32_e32 v47, v47, v62
	ds_bpermute_b32 v62, v87, v47
	s_waitcnt lgkmcnt(0)
	v_add_f32_e32 v47, v47, v62
	ds_bpermute_b32 v62, v88, v47
	s_waitcnt lgkmcnt(0)
; __device__ __forceinline__ float shx(float v, int o, int lane) { return __int_as_float(__builtin_amdgcn_ds_bpermute((lane ^ o) << 2, __float_as_int(v))); }
; __device__ __forceinline__ void attn_unit(LAS unsigned char* lds, bf16_t* Zg, const unsigned char* KVg, int S, int b, int h, int qb, const float* lq1, const float* lk1, const float* lq2, const float* lk2, const float* subln_g, const float* rel_bias, bool dostore = true) {
;     ...
;         for (int r = 0; r < 16; ++r) {
; #pragma unroll
;             for (int sft = 1; sft < 32; sft <<= 1) ss[r] += shx(ss[r], sft, lane);
;             ss[r] = (1.0f - LAMBDA_INIT) / sqrtf(ss[r] * (1.0f / 128.0f) + EPS); }
	v_add_f32_e32 v47, v47, v62
	v_fmamk_f32 v47, v47, 0x3c000000, v206
	v_cmp_gt_f32_e32 vcc, s36, v47
	v_mul_f32_e32 v62, 0x4f800000, v47
	s_nop 0
	v_cndmask_b32_e32 v47, v47, v62, vcc
	v_sqrt_f32_e32 v62, v47
	s_nop 0
	v_add_u32_e32 v66, -1, v62
	v_fma_f32 v67, -v66, v62, v47
	v_cmp_ge_f32_e64 s[4:5], 0, v67
	v_add_u32_e32 v67, 1, v62
	s_nop 0
	v_cndmask_b32_e64 v66, v62, v66, s[4:5]
	v_fma_f32 v62, -v67, v62, v47
	v_cmp_lt_f32_e64 s[4:5], 0, v62
	s_nop 1
	v_cndmask_b32_e64 v62, v66, v67, s[4:5]
	v_mul_f32_e32 v66, 0x37800000, v62
	v_cndmask_b32_e32 v62, v62, v66, vcc
	v_cmp_class_f32_e32 vcc, v47, v205
	s_nop 1
	v_cndmask_b32_e32 v47, v62, v47, vcc
	v_div_scale_f32 v62, s[4:5], v47, v47, s95
	v_rcp_f32_e32 v66, v62
	s_nop 0
	v_fma_f32 v67, -v62, v66, 1.0
	v_fmac_f32_e32 v66, v67, v66
	v_div_scale_f32 v67, vcc, s95, v47, s95
	v_mul_f32_e32 v69, v67, v66
	v_fma_f32 v99, -v62, v69, v67
	v_fmac_f32_e32 v69, v99, v66
	v_fma_f32 v62, -v62, v69, v67
	v_div_fmas_f32 v62, v62, v66, v69
	v_div_fixup_f32 v47, v62, v47, s95
	ds_bpermute_b32 v62, v84, v98
	v_mul_f32_e32 v80, v80, v47
	s_waitcnt lgkmcnt(0)
	v_add_f32_e32 v62, v98, v62
	ds_bpermute_b32 v66, v85, v62
	s_waitcnt lgkmcnt(0)
	v_add_f32_e32 v62, v62, v66
	ds_bpermute_b32 v66, v86, v62
	s_waitcnt lgkmcnt(0)
	v_add_f32_e32 v62, v62, v66
	ds_bpermute_b32 v66, v87, v62
	s_waitcnt lgkmcnt(0)
	v_add_f32_e32 v62, v62, v66
	ds_bpermute_b32 v66, v88, v62
	s_waitcnt lgkmcnt(0)
	v_add_f32_e32 v62, v62, v66
	v_fmamk_f32 v62, v62, 0x3c000000, v206
	v_cmp_gt_f32_e32 vcc, s36, v62
	v_mul_f32_e32 v66, 0x4f800000, v62
	s_nop 0
	v_cndmask_b32_e32 v62, v62, v66, vcc
	v_sqrt_f32_e32 v66, v62
	s_nop 0
	v_add_u32_e32 v67, -1, v66
	v_fma_f32 v69, -v67, v66, v62
	v_cmp_ge_f32_e64 s[4:5], 0, v69
	v_add_u32_e32 v69, 1, v66
	s_nop 0
	v_cndmask_b32_e64 v67, v66, v67, s[4:5]
	v_fma_f32 v66, -v69, v66, v62
	v_cmp_lt_f32_e64 s[4:5], 0, v66
	s_nop 1
	v_cndmask_b32_e64 v66, v67, v69, s[4:5]
	v_mul_f32_e32 v67, 0x37800000, v66
	v_cndmask_b32_e32 v66, v66, v67, vcc
	v_cmp_class_f32_e32 vcc, v62, v205
	s_nop 1
	v_cndmask_b32_e32 v62, v66, v62, vcc
	v_div_scale_f32 v66, s[4:5], v62, v62, s95
	v_rcp_f32_e32 v67, v66
	s_nop 0
	v_fma_f32 v69, -v66, v67, 1.0
	v_fmac_f32_e32 v67, v69, v67
	v_div_scale_f32 v69, vcc, s95, v62, s95
	v_mul_f32_e32 v98, v69, v67
	v_fma_f32 v99, -v66, v98, v69
	v_fmac_f32_e32 v98, v99, v67
	v_fma_f32 v66, -v66, v98, v69
	v_div_fmas_f32 v66, v66, v67, v98
	v_div_fixup_f32 v62, v66, v62, s95
	ds_bpermute_b32 v66, v84, v97
	v_mul_f32_e32 v81, v81, v62
	s_waitcnt lgkmcnt(0)
	v_add_f32_e32 v66, v97, v66
	ds_bpermute_b32 v67, v85, v66
	s_waitcnt lgkmcnt(0)
	v_add_f32_e32 v66, v66, v67
	ds_bpermute_b32 v67, v86, v66
	s_waitcnt lgkmcnt(0)
	v_add_f32_e32 v66, v66, v67
	ds_bpermute_b32 v67, v87, v66
	s_waitcnt lgkmcnt(0)
	v_add_f32_e32 v66, v66, v67
	ds_bpermute_b32 v67, v88, v66
	s_waitcnt lgkmcnt(0)
	v_add_f32_e32 v66, v66, v67
	v_fmamk_f32 v66, v66, 0x3c000000, v206
	v_cmp_gt_f32_e32 vcc, s36, v66
	v_mul_f32_e32 v67, 0x4f800000, v66
	s_nop 0
	v_cndmask_b32_e32 v66, v66, v67, vcc
	v_sqrt_f32_e32 v67, v66
	s_nop 0
	v_add_u32_e32 v69, -1, v67
	v_fma_f32 v97, -v69, v67, v66
	v_cmp_ge_f32_e64 s[4:5], 0, v97
	v_add_u32_e32 v97, 1, v67
	s_nop 0
	v_cndmask_b32_e64 v69, v67, v69, s[4:5]
	v_fma_f32 v67, -v97, v67, v66
	v_cmp_lt_f32_e64 s[4:5], 0, v67
	s_nop 1
	v_cndmask_b32_e64 v67, v69, v97, s[4:5]
	v_mul_f32_e32 v69, 0x37800000, v67
	v_cndmask_b32_e32 v67, v67, v69, vcc
	v_cmp_class_f32_e32 vcc, v66, v205
	s_nop 1
	v_cndmask_b32_e32 v66, v67, v66, vcc
	v_div_scale_f32 v67, s[4:5], v66, v66, s95
	v_rcp_f32_e32 v69, v67
	s_nop 0
	v_fma_f32 v97, -v67, v69, 1.0
	v_fmac_f32_e32 v69, v97, v69
	v_div_scale_f32 v97, vcc, s95, v66, s95
	v_mul_f32_e32 v98, v97, v69
	v_fma_f32 v99, -v67, v98, v97
	v_fmac_f32_e32 v98, v99, v69
	v_fma_f32 v67, -v67, v98, v97
	v_div_fmas_f32 v67, v67, v69, v98
	v_div_fixup_f32 v66, v67, v66, s95
	ds_bpermute_b32 v67, v84, v96
	v_mul_f32_e32 v74, v74, v66
	s_waitcnt lgkmcnt(0)
	v_add_f32_e32 v67, v96, v67
	ds_bpermute_b32 v69, v85, v67
	s_waitcnt lgkmcnt(0)
	v_add_f32_e32 v67, v67, v69
	ds_bpermute_b32 v69, v86, v67
	s_waitcnt lgkmcnt(0)
	v_add_f32_e32 v67, v67, v69
	ds_bpermute_b32 v69, v87, v67
	s_waitcnt lgkmcnt(0)
	v_add_f32_e32 v67, v67, v69
	ds_bpermute_b32 v69, v88, v67
	s_waitcnt lgkmcnt(0)
	v_add_f32_e32 v67, v67, v69
	v_fmamk_f32 v67, v67, 0x3c000000, v206
	v_cmp_gt_f32_e32 vcc, s36, v67
	v_mul_f32_e32 v69, 0x4f800000, v67
	s_nop 0
	v_cndmask_b32_e32 v67, v67, v69, vcc
	v_sqrt_f32_e32 v69, v67
	s_nop 0
	v_add_u32_e32 v96, -1, v69
	v_fma_f32 v97, -v96, v69, v67
	v_cmp_ge_f32_e64 s[4:5], 0, v97
	v_add_u32_e32 v97, 1, v69
	s_nop 0
	v_cndmask_b32_e64 v96, v69, v96, s[4:5]
	v_fma_f32 v69, -v97, v69, v67
	v_cmp_lt_f32_e64 s[4:5], 0, v69
	s_nop 1
	v_cndmask_b32_e64 v69, v96, v97, s[4:5]
	v_mul_f32_e32 v96, 0x37800000, v69
	v_cndmask_b32_e32 v69, v69, v96, vcc
	v_cmp_class_f32_e32 vcc, v67, v205
	s_nop 1
	v_cndmask_b32_e32 v67, v69, v67, vcc
	v_div_scale_f32 v69, s[4:5], v67, v67, s95
	v_rcp_f32_e32 v96, v69
	s_nop 0
	v_fma_f32 v97, -v69, v96, 1.0
	v_fmac_f32_e32 v96, v97, v96
	v_div_scale_f32 v97, vcc, s95, v67, s95
	v_mul_f32_e32 v98, v97, v96
	v_fma_f32 v99, -v69, v98, v97
	v_fmac_f32_e32 v98, v99, v96
	v_fma_f32 v69, -v69, v98, v97
	v_div_fmas_f32 v69, v69, v96, v98
	v_div_fixup_f32 v67, v69, v67, s95
	ds_bpermute_b32 v69, v84, v95
	v_mul_f32_e32 v75, v75, v67
	s_waitcnt lgkmcnt(0)
	v_add_f32_e32 v69, v95, v69
	ds_bpermute_b32 v95, v85, v69
	s_waitcnt lgkmcnt(0)
	v_add_f32_e32 v69, v69, v95
	ds_bpermute_b32 v95, v86, v69
	s_waitcnt lgkmcnt(0)
	v_add_f32_e32 v69, v69, v95
	ds_bpermute_b32 v95, v87, v69
	s_waitcnt lgkmcnt(0)
; __device__ __forceinline__ float shx(float v, int o, int lane) { return __int_as_float(__builtin_amdgcn_ds_bpermute((lane ^ o) << 2, __float_as_int(v))); }
; __device__ __forceinline__ void attn_unit(LAS unsigned char* lds, bf16_t* Zg, const unsigned char* KVg, int S, int b, int h, int qb, const float* lq1, const float* lk1, const float* lq2, const float* lk2, const float* subln_g, const float* rel_bias, bool dostore = true) {
;     ...
;         for (int r = 0; r < 16; ++r) {
; #pragma unroll
;             for (int sft = 1; sft < 32; sft <<= 1) ss[r] += shx(ss[r], sft, lane);
;             ss[r] = (1.0f - LAMBDA_INIT) / sqrtf(ss[r] * (1.0f / 128.0f) + EPS); }
	v_add_f32_e32 v69, v69, v95
	ds_bpermute_b32 v95, v88, v69
	s_waitcnt lgkmcnt(0)
	v_add_f32_e32 v69, v69, v95
	v_fmamk_f32 v69, v69, 0x3c000000, v206
	v_cmp_gt_f32_e32 vcc, s36, v69
	v_mul_f32_e32 v95, 0x4f800000, v69
	s_nop 0
	v_cndmask_b32_e32 v69, v69, v95, vcc
	v_sqrt_f32_e32 v95, v69
	s_nop 0
	v_add_u32_e32 v96, -1, v95
	v_fma_f32 v97, -v96, v95, v69
	v_cmp_ge_f32_e64 s[4:5], 0, v97
	v_add_u32_e32 v97, 1, v95
	s_nop 0
	v_cndmask_b32_e64 v96, v95, v96, s[4:5]
	v_fma_f32 v95, -v97, v95, v69
	v_cmp_lt_f32_e64 s[4:5], 0, v95
	s_nop 1
	v_cndmask_b32_e64 v95, v96, v97, s[4:5]
	v_mul_f32_e32 v96, 0x37800000, v95
	v_cndmask_b32_e32 v95, v95, v96, vcc
	v_cmp_class_f32_e32 vcc, v69, v205
	s_nop 1
	v_cndmask_b32_e32 v69, v95, v69, vcc
	v_div_scale_f32 v95, s[4:5], v69, v69, s95
	v_rcp_f32_e32 v96, v95
	s_nop 0
	v_fma_f32 v97, -v95, v96, 1.0
	v_fmac_f32_e32 v96, v97, v96
	v_div_scale_f32 v97, vcc, s95, v69, s95
	v_mul_f32_e32 v98, v97, v96
	v_fma_f32 v99, -v95, v98, v97
	v_fmac_f32_e32 v98, v99, v96
	v_fma_f32 v95, -v95, v98, v97
	v_div_fmas_f32 v95, v95, v96, v98
	v_div_fixup_f32 v69, v95, v69, s95
	ds_bpermute_b32 v95, v84, v90
	v_mul_f32_e32 v76, v76, v69
	v_mul_f32_e32 v25, v25, v69
	s_waitcnt lgkmcnt(0)
	v_add_f32_e32 v90, v90, v95
	ds_bpermute_b32 v95, v85, v90
	s_waitcnt lgkmcnt(0)
	v_add_f32_e32 v90, v90, v95
	ds_bpermute_b32 v95, v86, v90
	s_waitcnt lgkmcnt(0)
	v_add_f32_e32 v90, v90, v95
	ds_bpermute_b32 v95, v87, v90
	s_waitcnt lgkmcnt(0)
	v_add_f32_e32 v90, v90, v95
	ds_bpermute_b32 v95, v88, v90
	s_waitcnt lgkmcnt(0)
	v_add_f32_e32 v90, v90, v95
	v_fmamk_f32 v90, v90, 0x3c000000, v206
	v_cmp_gt_f32_e32 vcc, s36, v90
	v_mul_f32_e32 v95, 0x4f800000, v90
	s_nop 0
	v_cndmask_b32_e32 v90, v90, v95, vcc
	v_sqrt_f32_e32 v95, v90
	s_nop 0
	v_add_u32_e32 v96, -1, v95
	v_fma_f32 v97, -v96, v95, v90
	v_cmp_ge_f32_e64 s[4:5], 0, v97
	v_add_u32_e32 v97, 1, v95
	s_nop 0
	v_cndmask_b32_e64 v96, v95, v96, s[4:5]
	v_fma_f32 v95, -v97, v95, v90
	v_cmp_lt_f32_e64 s[4:5], 0, v95
	s_nop 1
	v_cndmask_b32_e64 v95, v96, v97, s[4:5]
	v_mul_f32_e32 v96, 0x37800000, v95
	v_cndmask_b32_e32 v95, v95, v96, vcc
	v_cmp_class_f32_e32 vcc, v90, v205
	s_nop 1
	v_cndmask_b32_e32 v90, v95, v90, vcc
	v_div_scale_f32 v95, s[4:5], v90, v90, s95
	v_rcp_f32_e32 v96, v95
	s_nop 0
	v_fma_f32 v97, -v95, v96, 1.0
	v_fmac_f32_e32 v96, v97, v96
	v_div_scale_f32 v97, vcc, s95, v90, s95
	v_mul_f32_e32 v98, v97, v96
	v_fma_f32 v99, -v95, v98, v97
	v_fmac_f32_e32 v98, v99, v96
	v_fma_f32 v95, -v95, v98, v97
	v_div_fmas_f32 v95, v95, v96, v98
	v_div_fixup_f32 v90, v95, v90, s95
	ds_bpermute_b32 v95, v84, v93
	v_mul_f32_e32 v77, v77, v90
	s_waitcnt lgkmcnt(0)
	v_add_f32_e32 v93, v93, v95
	ds_bpermute_b32 v95, v85, v93
	s_waitcnt lgkmcnt(0)
	v_add_f32_e32 v93, v93, v95
	ds_bpermute_b32 v95, v86, v93
	s_waitcnt lgkmcnt(0)
	v_add_f32_e32 v93, v93, v95
	ds_bpermute_b32 v95, v87, v93
	s_waitcnt lgkmcnt(0)
	v_add_f32_e32 v93, v93, v95
	ds_bpermute_b32 v95, v88, v93
	s_waitcnt lgkmcnt(0)
	v_add_f32_e32 v93, v93, v95
	v_fmamk_f32 v93, v93, 0x3c000000, v206
	v_cmp_gt_f32_e32 vcc, s36, v93
	v_mul_f32_e32 v95, 0x4f800000, v93
	s_nop 0
	v_cndmask_b32_e32 v93, v93, v95, vcc
	v_sqrt_f32_e32 v95, v93
	s_nop 0
	v_add_u32_e32 v96, -1, v95
	v_fma_f32 v97, -v96, v95, v93
	v_cmp_ge_f32_e64 s[4:5], 0, v97
	v_add_u32_e32 v97, 1, v95
	s_nop 0
	v_cndmask_b32_e64 v96, v95, v96, s[4:5]
	v_fma_f32 v95, -v97, v95, v93
	v_cmp_lt_f32_e64 s[4:5], 0, v95
	s_nop 1
	v_cndmask_b32_e64 v95, v96, v97, s[4:5]
	v_mul_f32_e32 v96, 0x37800000, v95
	v_cndmask_b32_e32 v95, v95, v96, vcc
	v_cmp_class_f32_e32 vcc, v93, v205
	s_nop 1
	v_cndmask_b32_e32 v93, v95, v93, vcc
	v_div_scale_f32 v95, s[4:5], v93, v93, s95
	v_rcp_f32_e32 v96, v95
	s_nop 0
	v_fma_f32 v97, -v95, v96, 1.0
	v_fmac_f32_e32 v96, v97, v96
	v_div_scale_f32 v97, vcc, s95, v93, s95
	v_mul_f32_e32 v98, v97, v96
	v_fma_f32 v99, -v95, v98, v97
	v_fmac_f32_e32 v98, v99, v96
	v_fma_f32 v95, -v95, v98, v97
	v_div_fmas_f32 v95, v95, v96, v98
	v_div_fixup_f32 v93, v95, v93, s95
	ds_bpermute_b32 v95, v84, v94
	v_mul_f32_e32 v70, v70, v93
	v_mul_f32_e32 v43, v43, v93
	s_waitcnt lgkmcnt(0)
	v_add_f32_e32 v94, v94, v95
	ds_bpermute_b32 v95, v85, v94
	s_waitcnt lgkmcnt(0)
	v_add_f32_e32 v94, v94, v95
	ds_bpermute_b32 v95, v86, v94
	s_waitcnt lgkmcnt(0)
	v_add_f32_e32 v94, v94, v95
	ds_bpermute_b32 v95, v87, v94
	s_waitcnt lgkmcnt(0)
	v_add_f32_e32 v94, v94, v95
	ds_bpermute_b32 v95, v88, v94
	s_waitcnt lgkmcnt(0)
	v_add_f32_e32 v94, v94, v95
	v_fmamk_f32 v94, v94, 0x3c000000, v206
	v_cmp_gt_f32_e32 vcc, s36, v94
	v_mul_f32_e32 v95, 0x4f800000, v94
	s_nop 0
	v_cndmask_b32_e32 v94, v94, v95, vcc
	v_sqrt_f32_e32 v95, v94
	s_nop 0
	v_add_u32_e32 v96, -1, v95
	v_fma_f32 v97, -v96, v95, v94
	v_cmp_ge_f32_e64 s[4:5], 0, v97
	v_add_u32_e32 v97, 1, v95
	s_nop 0
	v_cndmask_b32_e64 v96, v95, v96, s[4:5]
	v_fma_f32 v95, -v97, v95, v94
	v_cmp_lt_f32_e64 s[4:5], 0, v95
	s_nop 1
	v_cndmask_b32_e64 v95, v96, v97, s[4:5]
	v_mul_f32_e32 v96, 0x37800000, v95
	v_cndmask_b32_e32 v95, v95, v96, vcc
	v_cmp_class_f32_e32 vcc, v94, v205
	s_nop 1
	v_cndmask_b32_e32 v94, v95, v94, vcc
	v_div_scale_f32 v95, s[4:5], v94, v94, s95
	v_rcp_f32_e32 v96, v95
	s_nop 0
	v_fma_f32 v97, -v95, v96, 1.0
	v_fmac_f32_e32 v96, v97, v96
	v_div_scale_f32 v97, vcc, s95, v94, s95
	v_mul_f32_e32 v98, v97, v96
	v_fma_f32 v99, -v95, v98, v97
	v_fmac_f32_e32 v98, v99, v96
	v_fma_f32 v95, -v95, v98, v97
	v_div_fmas_f32 v95, v95, v96, v98
	v_div_fixup_f32 v94, v95, v94, s95
	ds_bpermute_b32 v95, v84, v92
	v_mul_f32_e32 v71, v71, v94
	s_waitcnt lgkmcnt(0)
	v_add_f32_e32 v92, v92, v95
	ds_bpermute_b32 v95, v85, v92
	s_waitcnt lgkmcnt(0)
; __device__ __forceinline__ float shx(float v, int o, int lane) { return __int_as_float(__builtin_amdgcn_ds_bpermute((lane ^ o) << 2, __float_as_int(v))); }
; __device__ __forceinline__ void attn_unit(LAS unsigned char* lds, bf16_t* Zg, const unsigned char* KVg, int S, int b, int h, int qb, const float* lq1, const float* lk1, const float* lq2, const float* lk2, const float* subln_g, const float* rel_bias, bool dostore = true) {
;     ...
;         for (int r = 0; r < 16; ++r) {
; #pragma unroll
;             for (int sft = 1; sft < 32; sft <<= 1) ss[r] += shx(ss[r], sft, lane);
;             ss[r] = (1.0f - LAMBDA_INIT) / sqrtf(ss[r] * (1.0f / 128.0f) + EPS); }
	v_add_f32_e32 v92, v92, v95
	ds_bpermute_b32 v95, v86, v92
	s_waitcnt lgkmcnt(0)
	v_add_f32_e32 v92, v92, v95
	ds_bpermute_b32 v95, v87, v92
	s_waitcnt lgkmcnt(0)
	v_add_f32_e32 v92, v92, v95
	ds_bpermute_b32 v95, v88, v92
	s_waitcnt lgkmcnt(0)
	v_add_f32_e32 v92, v92, v95
	v_fmamk_f32 v92, v92, 0x3c000000, v206
	v_cmp_gt_f32_e32 vcc, s36, v92
	v_mul_f32_e32 v95, 0x4f800000, v92
	s_nop 0
	v_cndmask_b32_e32 v92, v92, v95, vcc
	v_sqrt_f32_e32 v95, v92
	s_nop 0
	v_add_u32_e32 v96, -1, v95
	v_fma_f32 v97, -v96, v95, v92
	v_cmp_ge_f32_e64 s[4:5], 0, v97
	v_add_u32_e32 v97, 1, v95
	s_nop 0
	v_cndmask_b32_e64 v96, v95, v96, s[4:5]
	v_fma_f32 v95, -v97, v95, v92
	v_cmp_lt_f32_e64 s[4:5], 0, v95
	s_nop 1
	v_cndmask_b32_e64 v95, v96, v97, s[4:5]
	v_mul_f32_e32 v96, 0x37800000, v95
	v_cndmask_b32_e32 v95, v95, v96, vcc
	v_cmp_class_f32_e32 vcc, v92, v205
	s_nop 1
	v_cndmask_b32_e32 v92, v95, v92, vcc
	v_div_scale_f32 v95, s[4:5], v92, v92, s95
	v_rcp_f32_e32 v96, v95
	s_nop 0
	v_fma_f32 v97, -v95, v96, 1.0
	v_fmac_f32_e32 v96, v97, v96
	v_div_scale_f32 v97, vcc, s95, v92, s95
	v_mul_f32_e32 v98, v97, v96
	v_fma_f32 v99, -v95, v98, v97
	v_fmac_f32_e32 v98, v99, v96
	v_fma_f32 v95, -v95, v98, v97
	v_div_fmas_f32 v95, v95, v96, v98
	v_div_fixup_f32 v92, v95, v92, s95
	ds_bpermute_b32 v95, v84, v91
	v_mul_f32_e32 v61, v61, v92
	s_waitcnt lgkmcnt(0)
	v_add_f32_e32 v91, v91, v95
	ds_bpermute_b32 v95, v85, v91
	s_waitcnt lgkmcnt(0)
	v_add_f32_e32 v91, v91, v95
	ds_bpermute_b32 v95, v86, v91
	s_waitcnt lgkmcnt(0)
	v_add_f32_e32 v91, v91, v95
	ds_bpermute_b32 v95, v87, v91
	s_waitcnt lgkmcnt(0)
	v_add_f32_e32 v91, v91, v95
	ds_bpermute_b32 v95, v88, v91
	s_waitcnt lgkmcnt(0)
	v_add_f32_e32 v91, v91, v95
	v_fmamk_f32 v91, v91, 0x3c000000, v206
	v_cmp_gt_f32_e32 vcc, s36, v91
	v_mul_f32_e32 v95, 0x4f800000, v91
	s_nop 0
	v_cndmask_b32_e32 v91, v91, v95, vcc
	v_sqrt_f32_e32 v95, v91
	s_nop 0
	v_add_u32_e32 v96, -1, v95
	v_fma_f32 v97, -v96, v95, v91
	v_cmp_ge_f32_e64 s[4:5], 0, v97
	v_add_u32_e32 v97, 1, v95
	s_nop 0
	v_cndmask_b32_e64 v96, v95, v96, s[4:5]
	v_fma_f32 v95, -v97, v95, v91
	v_cmp_lt_f32_e64 s[4:5], 0, v95
	s_nop 1
	v_cndmask_b32_e64 v95, v96, v97, s[4:5]
	v_mul_f32_e32 v96, 0x37800000, v95
	v_cndmask_b32_e32 v95, v95, v96, vcc
	v_cmp_class_f32_e32 vcc, v91, v205
	s_nop 1
	v_cndmask_b32_e32 v91, v95, v91, vcc
	v_div_scale_f32 v95, s[4:5], v91, v91, s95
	v_rcp_f32_e32 v96, v95
	s_nop 0
	v_fma_f32 v97, -v95, v96, 1.0
	v_fmac_f32_e32 v96, v97, v96
	v_div_scale_f32 v97, vcc, s95, v91, s95
	v_mul_f32_e32 v98, v97, v96
	v_fma_f32 v99, -v95, v98, v97
	v_fmac_f32_e32 v98, v99, v96
	v_fma_f32 v95, -v95, v98, v97
	v_div_fmas_f32 v95, v95, v96, v98
	v_div_fixup_f32 v91, v95, v91, s95
	ds_bpermute_b32 v95, v84, v89
	v_mul_f32_e32 v72, v72, v91
	s_waitcnt lgkmcnt(0)
	v_add_f32_e32 v89, v89, v95
	ds_bpermute_b32 v95, v85, v89
	s_waitcnt lgkmcnt(0)
	v_add_f32_e32 v89, v89, v95
	ds_bpermute_b32 v95, v86, v89
	s_waitcnt lgkmcnt(0)
	v_add_f32_e32 v89, v89, v95
	ds_bpermute_b32 v95, v87, v89
	s_waitcnt lgkmcnt(0)
	v_add_f32_e32 v89, v89, v95
	ds_bpermute_b32 v95, v88, v89
	s_waitcnt lgkmcnt(0)
	v_add_f32_e32 v89, v89, v95
	v_fmamk_f32 v89, v89, 0x3c000000, v206
	v_cmp_gt_f32_e32 vcc, s36, v89
	v_mul_f32_e32 v95, 0x4f800000, v89
	s_nop 0
	v_cndmask_b32_e32 v89, v89, v95, vcc
	v_sqrt_f32_e32 v95, v89
	s_nop 0
	v_add_u32_e32 v96, -1, v95
	v_fma_f32 v97, -v96, v95, v89
	v_cmp_ge_f32_e64 s[4:5], 0, v97
	v_add_u32_e32 v97, 1, v95
	s_nop 0
	v_cndmask_b32_e64 v96, v95, v96, s[4:5]
	v_fma_f32 v95, -v97, v95, v89
	v_cmp_lt_f32_e64 s[4:5], 0, v95
	s_nop 1
	v_cndmask_b32_e64 v95, v96, v97, s[4:5]
	v_mul_f32_e32 v96, 0x37800000, v95
	v_cndmask_b32_e32 v95, v95, v96, vcc
	v_cmp_class_f32_e32 vcc, v89, v205
	s_nop 1
	v_cndmask_b32_e32 v89, v95, v89, vcc
	v_div_scale_f32 v95, s[4:5], v89, v89, s95
	v_rcp_f32_e32 v96, v95
	s_nop 0
	v_fma_f32 v97, -v95, v96, 1.0
	v_fmac_f32_e32 v96, v97, v96
	v_div_scale_f32 v97, vcc, s95, v89, s95
	v_mul_f32_e32 v98, v97, v96
	v_fma_f32 v99, -v95, v98, v97
	v_fmac_f32_e32 v98, v99, v96
	v_fma_f32 v95, -v95, v98, v97
	v_div_fmas_f32 v95, v95, v96, v98
	v_div_fixup_f32 v89, v95, v89, s95
	ds_bpermute_b32 v95, v84, v73
	ds_bpermute_b32 v84, v84, v68
	v_mul_f32_e32 v63, v63, v89
	s_waitcnt lgkmcnt(1)
	v_add_f32_e32 v73, v73, v95
	ds_bpermute_b32 v95, v85, v73
	s_waitcnt lgkmcnt(1)
	v_add_f32_e32 v68, v68, v84
	ds_bpermute_b32 v84, v85, v68
	s_waitcnt lgkmcnt(1)
	v_add_f32_e32 v73, v73, v95
	ds_bpermute_b32 v95, v86, v73
	s_waitcnt lgkmcnt(1)
	v_add_f32_e32 v68, v68, v84
	ds_bpermute_b32 v84, v86, v68
	s_waitcnt lgkmcnt(1)
	v_add_f32_e32 v73, v73, v95
	ds_bpermute_b32 v95, v87, v73
	s_waitcnt lgkmcnt(1)
	v_add_f32_e32 v68, v68, v84
	ds_bpermute_b32 v84, v87, v68
	s_waitcnt lgkmcnt(1)
	v_add_f32_e32 v73, v73, v95
	ds_bpermute_b32 v95, v88, v73
	s_waitcnt lgkmcnt(1)
	v_add_f32_e32 v68, v68, v84
	ds_bpermute_b32 v84, v88, v68
	s_waitcnt lgkmcnt(1)
	v_add_f32_e32 v73, v73, v95
	v_fmamk_f32 v73, v73, 0x3c000000, v206
	v_cmp_gt_f32_e32 vcc, s36, v73
	v_mul_f32_e32 v95, 0x4f800000, v73
	s_waitcnt lgkmcnt(0)
; __device__ __forceinline__ float shx(float v, int o, int lane) { return __int_as_float(__builtin_amdgcn_ds_bpermute((lane ^ o) << 2, __float_as_int(v))); }
; __device__ __forceinline__ int crow(int r, int hi) { return (r & 3) + 8 * (r >> 2) + 4 * hi; }
; __device__ __forceinline__ void attn_unit(LAS unsigned char* lds, bf16_t* Zg, const unsigned char* KVg, int S, int b, int h, int qb, const float* lq1, const float* lk1, const float* lq2, const float* lk2, const float* subln_g, const float* rel_bias, bool dostore = true) {
;     ...
;         for (int r = 0; r < 16; ++r) {
; #pragma unroll
;             for (int sft = 1; sft < 32; sft <<= 1) ss[r] += shx(ss[r], sft, lane);
;             ss[r] = (1.0f - LAMBDA_INIT) / sqrtf(ss[r] * (1.0f / 128.0f) + EPS); }
; #pragma unroll
;         for (int db = 0; db < 4; ++db) { const float sg = subln_g[db * 32 + r32];
; #pragma unroll
;             for (int r = 0; r < 16; ++r) exch[(32 * qsub + crow(r, hi)) * 128 + db * 32 + r32] = o[db][r] * ss[r] * sg; }
	v_add_f32_e32 v68, v68, v84
	v_cndmask_b32_e32 v73, v73, v95, vcc
	v_sqrt_f32_e32 v95, v73
	v_fmamk_f32 v68, v68, 0x3c000000, v206
	v_mul_f32_e32 v84, 0x4f800000, v68
	v_add_u32_e32 v96, -1, v95
	v_fma_f32 v97, -v96, v95, v73
	v_cmp_ge_f32_e64 s[4:5], 0, v97
	v_add_u32_e32 v97, 1, v95
	s_nop 0
	v_cndmask_b32_e64 v96, v95, v96, s[4:5]
	v_fma_f32 v95, -v97, v95, v73
	v_cmp_lt_f32_e64 s[4:5], 0, v95
	s_nop 1
	v_cndmask_b32_e64 v95, v96, v97, s[4:5]
	v_mul_f32_e32 v96, 0x37800000, v95
	v_cndmask_b32_e32 v95, v95, v96, vcc
	v_cmp_class_f32_e32 vcc, v73, v205
	s_nop 1
	v_cndmask_b32_e32 v73, v95, v73, vcc
	v_div_scale_f32 v95, s[4:5], v73, v73, s95
	v_rcp_f32_e32 v96, v95
	s_nop 0
	v_fma_f32 v97, -v95, v96, 1.0
	v_fmac_f32_e32 v96, v97, v96
	v_div_scale_f32 v97, vcc, s95, v73, s95
	v_mul_f32_e32 v98, v97, v96
	v_fma_f32 v99, -v95, v98, v97
	v_fmac_f32_e32 v98, v99, v96
	v_fma_f32 v95, -v95, v98, v97
	v_div_fmas_f32 v95, v95, v96, v98
	v_cmp_gt_f32_e32 vcc, s36, v68
	v_div_fixup_f32 v73, v95, v73, s95
	v_mul_f32_e32 v64, v64, v73
	v_cndmask_b32_e32 v68, v68, v84, vcc
	v_sqrt_f32_e32 v84, v68
	s_nop 0
	v_add_u32_e32 v85, -1, v84
	v_fma_f32 v86, -v85, v84, v68
	v_cmp_ge_f32_e64 s[4:5], 0, v86
	v_add_u32_e32 v86, 1, v84
	s_nop 0
	v_cndmask_b32_e64 v85, v84, v85, s[4:5]
	v_fma_f32 v84, -v86, v84, v68
	v_cmp_lt_f32_e64 s[4:5], 0, v84
	s_nop 1
	v_cndmask_b32_e64 v84, v85, v86, s[4:5]
	v_mul_f32_e32 v85, 0x37800000, v84
	v_cndmask_b32_e32 v84, v84, v85, vcc
	v_cmp_class_f32_e32 vcc, v68, v205
	s_nop 1
	v_cndmask_b32_e32 v68, v84, v68, vcc
	v_div_scale_f32 v84, s[4:5], v68, v68, s95
	v_rcp_f32_e32 v85, v84
	s_nop 0
	v_fma_f32 v86, -v84, v85, 1.0
	v_fmac_f32_e32 v85, v86, v85
	v_div_scale_f32 v86, vcc, s95, v68, s95
	v_mul_f32_e32 v87, v86, v85
	v_fma_f32 v88, -v84, v87, v86
	v_fmac_f32_e32 v87, v88, v85
	v_fma_f32 v84, -v84, v87, v86
	v_div_fmas_f32 v84, v84, v85, v87
	v_div_fixup_f32 v68, v84, v68, s95
	global_load_dword v84, v82, s[68:69]
	global_load_dword v85, v82, s[68:69] offset:128
	global_load_dword v86, v82, s[68:69] offset:256
	global_load_dword v87, v82, s[68:69] offset:384
	v_mul_f32_e32 v65, v65, v68
	s_waitcnt vmcnt(0)
	v_mul_f32_e32 v83, v83, v84
	v_mul_f32_e32 v78, v78, v84
	v_mul_f32_e32 v79, v79, v84
	v_mul_f32_e32 v80, v80, v84
	v_mul_f32_e32 v81, v81, v84
	v_mul_f32_e32 v74, v74, v84
	v_mul_f32_e32 v75, v75, v84
	v_mul_f32_e32 v76, v76, v84
	v_mul_f32_e32 v77, v77, v84
	v_mul_f32_e32 v70, v70, v84
	v_mul_f32_e32 v71, v71, v84
	v_mul_f32_e32 v61, v61, v84
	v_mul_f32_e32 v72, v72, v84
	v_mul_f32_e32 v63, v63, v84
	v_mul_f32_e32 v64, v84, v64
	v_mul_f32_e32 v65, v84, v65
	v_mul_f32_e32 v50, v50, v85
	ds_write2_b32 v0, v83, v50 offset1:32
	v_mul_f32_e32 v50, v51, v30
	v_mul_f32_e32 v50, v50, v85
	ds_write2_b32 v0, v78, v50 offset0:128 offset1:160
	v_mul_f32_e32 v50, v52, v44
	v_mul_f32_e32 v50, v50, v85
	ds_write2_b32 v18, v79, v50 offset1:32
	v_mul_f32_e32 v50, v53, v47
	v_mul_f32_e32 v50, v50, v85
	ds_write2_b32 v18, v80, v50 offset0:128 offset1:160
	v_mul_f32_e32 v50, v54, v62
	v_mul_f32_e32 v43, v43, v85
	v_mul_f32_e32 v50, v50, v85
	ds_write2_b32 v21, v70, v43 offset0:128 offset1:160
	v_mul_f32_e32 v43, v59, v94
	ds_write2_b32 v19, v81, v50 offset1:32
	v_mul_f32_e32 v50, v55, v66
	v_mul_f32_e32 v43, v43, v85
	v_mul_f32_e32 v50, v50, v85
	ds_write2_b32 v22, v71, v43 offset1:32
	v_mul_f32_e32 v43, v45, v92
	ds_write2_b32 v19, v74, v50 offset0:128 offset1:160
	v_mul_f32_e32 v50, v56, v67
	v_mul_f32_e32 v43, v43, v85
	v_mul_f32_e32 v50, v50, v85
	ds_write2_b32 v22, v61, v43 offset0:128 offset1:160
	v_mul_f32_e32 v43, v46, v91
	ds_write2_b32 v20, v75, v50 offset1:32
	v_mul_f32_e32 v50, v57, v69
	v_mul_f32_e32 v43, v43, v85
	v_mul_f32_e32 v50, v50, v85
	ds_write2_b32 v23, v72, v43 offset1:32
	v_mul_f32_e32 v43, v60, v89
	ds_write2_b32 v20, v76, v50 offset0:128 offset1:160
	v_mul_f32_e32 v50, v58, v90
	v_mul_f32_e32 v43, v43, v85
	v_mul_f32_e32 v50, v50, v85
	ds_write2_b32 v23, v63, v43 offset0:128 offset1:160
	v_mul_f32_e32 v43, v48, v73
	ds_write2_b32 v21, v77, v50 offset1:32
	v_mul_f32_e32 v43, v43, v85
	ds_write2_b32 v15, v64, v43 offset1:32
	v_mul_f32_e32 v43, v49, v68
	v_mul_f32_e32 v43, v43, v85
	ds_write2_b32 v15, v65, v43 offset0:128 offset1:160
	v_mul_f32_e32 v50, v34, v86
	v_mul_f32_e32 v34, v35, v30
	v_mul_f32_e32 v49, v34, v86
	v_mul_f32_e32 v34, v36, v44
	v_mul_f32_e32 v48, v34, v86
	v_mul_f32_e32 v34, v37, v47
	v_mul_f32_e32 v46, v34, v86
	v_mul_f32_e32 v34, v38, v62
	v_mul_f32_e32 v38, v25, v86
	v_mul_f32_e32 v25, v26, v90
	v_mul_f32_e32 v37, v25, v86
	v_mul_f32_e32 v25, v41, v93
	v_mul_f32_e32 v45, v34, v86
	v_mul_f32_e32 v34, v39, v66
	v_mul_f32_e32 v36, v25, v86
	v_mul_f32_e32 v25, v28, v94
	v_mul_f32_e32 v43, v34, v86
	v_mul_f32_e32 v34, v40, v67
	v_mul_f32_e32 v35, v25, v86
	v_mul_f32_e32 v25, v29, v92
	v_mul_f32_e32 v39, v34, v86
	v_mul_f32_e32 v34, v25, v86
	v_mul_f32_e32 v25, v42, v91
	v_mul_f32_e32 v29, v25, v86
	v_mul_f32_e32 v25, v31, v89
	v_mul_f32_e32 v28, v25, v86
	v_mul_f32_e32 v25, v32, v73
	v_mul_f32_e32 v26, v25, v86
	v_mul_f32_e32 v25, v33, v68
	v_mul_f32_e32 v25, v25, v86
	v_mul_f32_e32 v2, v2, v87
	ds_write2_b32 v0, v50, v2 offset0:64 offset1:96
	v_mul_f32_e32 v2, v3, v30
	v_mul_f32_e32 v2, v2, v87
	ds_write2_b32 v0, v49, v2 offset0:192 offset1:224
	v_mul_f32_e32 v0, v4, v44
	v_mul_f32_e32 v0, v0, v87
	ds_write2_b32 v18, v48, v0 offset0:64 offset1:96
	v_mul_f32_e32 v0, v5, v47
	v_mul_f32_e32 v0, v0, v87
	ds_write2_b32 v18, v46, v0 offset0:192 offset1:224
	v_mul_f32_e32 v0, v6, v62
	v_mul_f32_e32 v0, v0, v87
	ds_write2_b32 v19, v45, v0 offset0:64 offset1:96
	v_mul_f32_e32 v0, v7, v66
	v_mul_f32_e32 v0, v0, v87
	ds_write2_b32 v19, v43, v0 offset0:192 offset1:224
	v_mul_f32_e32 v0, v8, v67
	v_mul_f32_e32 v0, v0, v87
	ds_write2_b32 v20, v39, v0 offset0:64 offset1:96
	v_mul_f32_e32 v0, v9, v69
	v_mul_f32_e32 v0, v0, v87
	ds_write2_b32 v20, v38, v0 offset0:192 offset1:224
	v_mul_f32_e32 v0, v10, v90
	v_mul_f32_e32 v0, v0, v87
	ds_write2_b32 v21, v37, v0 offset0:64 offset1:96
	v_mul_f32_e32 v0, v11, v93
	v_mul_f32_e32 v0, v0, v87
	ds_write2_b32 v21, v36, v0 offset0:192 offset1:224
	v_mul_f32_e32 v0, v12, v94
	v_mul_f32_e32 v0, v0, v87
	ds_write2_b32 v22, v35, v0 offset0:64 offset1:96
	v_mul_f32_e32 v0, v13, v92
	v_mul_f32_e32 v0, v0, v87
	ds_write2_b32 v22, v34, v0 offset0:192 offset1:224
	v_mul_f32_e32 v0, v14, v91
	v_mul_f32_e32 v0, v0, v87
	ds_write2_b32 v23, v29, v0 offset0:64 offset1:96
	v_mul_f32_e32 v0, v24, v89
	v_mul_f32_e32 v0, v0, v87
	ds_write2_b32 v23, v28, v0 offset0:192 offset1:224
	v_mul_f32_e32 v0, v16, v73
	v_mul_f32_e32 v0, v0, v87
	ds_write2_b32 v15, v26, v0 offset0:64 offset1:96
	v_mul_f32_e32 v0, v17, v68
	v_mul_f32_e32 v0, v0, v87
	ds_write2_b32 v15, v25, v0 offset0:192 offset1:224
	s_branch .LBB0_187
